# v37: no L2 write-back at the barrier after P5 (all P5 stores are write-through)
# baseline (speedup 1.0000x reference)
; __device__ __forceinline__ unsigned xb_ld(unsigned* p)              { return __hip_atomic_load(p, __ATOMIC_RELAXED, __HIP_MEMORY_SCOPE_AGENT); }
; __device__ __forceinline__ unsigned xb_add(unsigned* p, unsigned v) { return __hip_atomic_fetch_add(p, v, __ATOMIC_RELAXED, __HIP_MEMORY_SCOPE_AGENT); }
; #define XB_SPIN(cond, bar) do { unsigned _sp = 0; while (cond) { __builtin_amdgcn_s_sleep(1); \
;     if ((++_sp & 255u) == 0u) { if (xb_ld(&(bar)[XB_TMO])) break; if (_sp > XB_SPIN_CAP) { atomicAdd(&(bar)[XB_TMO], 1u); break; } } } } while (0)
; __device__ __forceinline__ void xcd_barrier(const XcdBarrier& b) {
;     ...
;         const unsigned old = xb_add(&bar[XB_XSUB(b.x)], 1u);
;         const unsigned gen = old / nloc;
;         if (old + 1u == (gen + 1u) * nloc) {
;             __builtin_amdgcn_fence(__ATOMIC_RELEASE, "agent");
;             asm volatile("s_waitcnt vmcnt(0)" ::: "memory");
;             const unsigned og = xb_add(&bar[XB_TOP], 1u);
;             const unsigned tg = og / nx;
;             if (og + 1u == (tg + 1u) * nx) xb_add(&bar[XB_TOPGEN], 1u);
;             else XB_SPIN(xb_ld(&bar[XB_TOPGEN]) == tg, bar);
;             __builtin_amdgcn_fence(__ATOMIC_ACQUIRE, "agent");
;             xb_add(&bar[XB_XGEN(b.x)], 1u);
;             asm volatile("s_waitcnt vmcnt(0)" ::: "memory");
.Lxb5_have:
	s_mov_b64 exec, 1
	v_readlane_b32 s99, v252, 2
	s_lshl_b32 s99, s99, 8
	s_add_u32 s99, s99, 0x1400
	v_mov_b32_e32 v254, s99
	v_mov_b32_e32 v255, 1
	global_atomic_add v255, v254, v255, s[68:69] sc0
	v_readlane_b32 s99, v253, 2
	s_add_u32 s99, s99, 1
	v_writelane_b32 v253, s99, 2
	s_mul_i32 s98, s98, s99
	s_waitcnt vmcnt(0)
	v_readfirstlane_b32 vcc_lo, v255
	s_add_u32 vcc_lo, vcc_lo, 1
	s_cmp_lg_u32 vcc_lo, s98
	s_cbranch_scc1 .Lxb5_wait
	v_mov_b32_e32 v254, 0x3400
	v_mov_b32_e32 v255, 1
	global_atomic_add v254, v255, s[68:69]
	s_branch .Lxb5_wait2
